# resid epilogue: X-new f32 stores write-through (sc1) so the grid barrier's L2 write-back has less dirty data
# baseline (speedup 1.0000x reference)
; __device__ __forceinline__ unsigned cvt_pk_bf16(float lo, float hi) { unsigned r; asm volatile("v_cvt_pk_bf16_f32 %0, %1, %2" : "=v"(r) : "v"(lo), "v"(hi)); return r; }
;     __device__ __forceinline__ void operator()(const f32x4 (&acc)[2][2][4][2], const Unit& u, int wr, int wc, int fr, int fq) const {
;     ...
;             const f32x4 g0 = *(const f32x4*)(gate + c), g1 = *(const f32x4*)(gate + c + 4), n0 = *(const f32x4*)(gn + c), n1 = *(const f32x4*)(gn + c + 4);
;             const f32x4 b0 = bias ? *(const f32x4*)(bias + c) : (f32x4){0.f, 0.f, 0.f, 0.f}, b1 = bias ? *(const f32x4*)(bias + c + 4) : (f32x4){0.f, 0.f, 0.f, 0.f};
; #pragma unroll
;             for (int ai = 0; ai < 2; ++ai) {
;                 f32x4 xa[4][2];
; #pragma unroll
;                 for (int m = 0; m < 4; ++m) { const unsigned off = (unsigned)(row0 + ai * HALF + m * 16) * 1024u + (unsigned)c; xa[m][0] = *(const f32x4*)(xold + off); xa[m][1] = *(const f32x4*)(xold + off + 4); }
; #pragma unroll
;                 for (int m = 0; m < 4; ++m) {
;                     const unsigned off = (unsigned)(row0 + ai * HALF + m * 16) * 1024u + (unsigned)c;
;                     const f32x4 x0 = xa[m][0], x1 = xa[m][1];
;                     const f32x4 y0 = x0 + g0 * (acc[ai][bj][m][0] + b0), y1 = x1 + g1 * (acc[ai][bj][m][1] + b1);
;                     if (!dry) { *(f32x4*)(xnew + off) = y0; *(f32x4*)(xnew + off + 4) = y1; }
;                     ss[ai][m] += (y0[0] * y0[0] + y0[1] * y0[1]) + (y0[2] * y0[2] + y0[3] * y0[3]) + (y1[0] * y1[0] + y1[1] * y1[1]) + (y1[2] * y1[2] + y1[3] * y1[3]);
;                     asm volatile("" : "+v"(ss[ai][m]));
;                     const f32x4 z0 = y0 * n0, z1 = y1 * n1;
;                     u32x4 w; w.x = cvt_pk_bf16(z0[0], z0[1]); w.y = cvt_pk_bf16(z0[2], z0[3]); w.z = cvt_pk_bf16(z1[0], z1[1]); w.w = cvt_pk_bf16(z1[2], z1[3]);
;                     if (!dry && xb) *(u32x4*)(xb + off) = w;
.Lre_nobias:
	s_cmp_lg_u64 s[76:77], 0
	s_cselect_b64 vcc, -1, 0
	s_add_u32 s44, s66, 0x0
	s_addc_u32 s45, s67, 0
	global_load_dwordx4 v[144:147], v180, s[44:45]
	global_load_dwordx4 v[148:151], v181, s[44:45]
	s_add_u32 s44, s66, 0x10000
	s_addc_u32 s45, s67, 0
	global_load_dwordx4 v[152:155], v180, s[44:45]
	global_load_dwordx4 v[156:159], v181, s[44:45]
	s_add_u32 s44, s66, 0x20000
	s_addc_u32 s45, s67, 0
	global_load_dwordx4 v[160:163], v180, s[44:45]
	global_load_dwordx4 v[164:167], v181, s[44:45]
	s_add_u32 s44, s66, 0x30000
	s_addc_u32 s45, s67, 0
	global_load_dwordx4 v[168:171], v180, s[44:45]
	global_load_dwordx4 v[172:175], v181, s[44:45]
	s_add_u32 s44, s66, 0x80000
	s_addc_u32 s45, s67, 0
	global_load_dwordx4 v[176:179], v180, s[44:45]
	global_load_dwordx4 v[196:199], v181, s[44:45]
	s_add_u32 s44, s66, 0x90000
	s_addc_u32 s45, s67, 0
	global_load_dwordx4 v[200:203], v180, s[44:45]
	global_load_dwordx4 v[204:207], v181, s[44:45]
	s_add_u32 s44, s66, 0xa0000
	s_addc_u32 s45, s67, 0
	global_load_dwordx4 v[208:211], v180, s[44:45]
	global_load_dwordx4 v[232:235], v181, s[44:45]
	s_add_u32 s44, s66, 0xb0000
	s_addc_u32 s45, s67, 0
	global_load_dwordx4 v[236:239], v180, s[44:45]
	global_load_dwordx4 v[240:243], v181, s[44:45]
	ds_write_b128 v130, v[126:129]
	ds_write_b128 v130, v[122:125] offset:16
	ds_read_b128 v[126:129], v131
	ds_read_b128 v[122:125], v131 offset:1152
	ds_write_b128 v130, v[110:113]
	ds_write_b128 v130, v[102:105] offset:16
	ds_read_b128 v[110:113], v131
	ds_read_b128 v[102:105], v131 offset:1152
	ds_write_b128 v130, v[94:97]
	ds_write_b128 v130, v[86:89] offset:16
	ds_read_b128 v[94:97], v131
	ds_read_b128 v[86:89], v131 offset:1152
	ds_write_b128 v130, v[78:81]
	ds_write_b128 v130, v[70:73] offset:16
	ds_read_b128 v[78:81], v131
	ds_read_b128 v[70:73], v131 offset:1152
	s_waitcnt vmcnt(8) lgkmcnt(0)
	v_pk_add_f32 v[126:127], v[126:127], v[136:137]
	v_pk_add_f32 v[128:129], v[128:129], v[138:139]
	v_pk_add_f32 v[122:123], v[122:123], v[136:137]
	v_pk_add_f32 v[124:125], v[124:125], v[138:139]
	s_add_u32 s44, s60, 0x0
	s_addc_u32 s45, s61, 0
	v_pk_fma_f32 v[144:145], v[132:133], v[126:127], v[144:145]
	v_pk_fma_f32 v[146:147], v[134:135], v[128:129], v[146:147]
	v_pk_fma_f32 v[148:149], v[132:133], v[122:123], v[148:149]
	v_pk_fma_f32 v[150:151], v[134:135], v[124:125], v[150:151]
	global_store_dwordx4 v180, v[144:147], s[44:45] sc1
	global_store_dwordx4 v181, v[148:151], s[44:45] sc1
	v_pk_mul_f32 v[126:127], v[140:141], v[144:145]
	v_pk_mul_f32 v[128:129], v[142:143], v[146:147]
	v_pk_mul_f32 v[122:123], v[140:141], v[148:149]
	v_pk_mul_f32 v[124:125], v[142:143], v[150:151]
	v_mul_f32_e32 v231, v145, v145
	v_mul_f32_e32 v244, v147, v147
	v_fmac_f32_e32 v231, v144, v144
	v_fmac_f32_e32 v244, v146, v146
	v_cvt_pk_bf16_f32 v126, v126, v127
	v_cvt_pk_bf16_f32 v127, v128, v129
	v_add_f32_e32 v128, v231, v244
	v_cvt_pk_bf16_f32 v122, v122, v123
	v_cvt_pk_bf16_f32 v123, v124, v125
	v_mul_f32_e32 v231, v149, v149
	v_mul_f32_e32 v244, v151, v151
	v_fmac_f32_e32 v231, v148, v148
	v_fmac_f32_e32 v244, v150, v150
	s_add_u32 s100, s64, 0x0
	s_addc_u32 s101, s65, 0
	v_add_f32_e32 v124, v231, v244
	s_cbranch_vccz .Lre_nx0_0
	global_store_dwordx2 v194, v[126:127], s[100:101]
	global_store_dwordx2 v195, v[122:123], s[100:101]
; __device__ __forceinline__ unsigned cvt_pk_bf16(float lo, float hi) { unsigned r; asm volatile("v_cvt_pk_bf16_f32 %0, %1, %2" : "=v"(r) : "v"(lo), "v"(hi)); return r; }
;     __device__ __forceinline__ void operator()(const f32x4 (&acc)[2][2][4][2], const Unit& u, int wr, int wc, int fr, int fq) const {
;     ...
;                 for (int m = 0; m < 4; ++m) {
;                     const unsigned off = (unsigned)(row0 + ai * HALF + m * 16) * 1024u + (unsigned)c;
;                     const f32x4 x0 = xa[m][0], x1 = xa[m][1];
;                     const f32x4 y0 = x0 + g0 * (acc[ai][bj][m][0] + b0), y1 = x1 + g1 * (acc[ai][bj][m][1] + b1);
;                     if (!dry) { *(f32x4*)(xnew + off) = y0; *(f32x4*)(xnew + off + 4) = y1; }
;                     ss[ai][m] += (y0[0] * y0[0] + y0[1] * y0[1]) + (y0[2] * y0[2] + y0[3] * y0[3]) + (y1[0] * y1[0] + y1[1] * y1[1]) + (y1[2] * y1[2] + y1[3] * y1[3]);
;                     asm volatile("" : "+v"(ss[ai][m]));
;                     const f32x4 z0 = y0 * n0, z1 = y1 * n1;
;                     u32x4 w; w.x = cvt_pk_bf16(z0[0], z0[1]); w.y = cvt_pk_bf16(z0[2], z0[3]); w.z = cvt_pk_bf16(z1[0], z1[1]); w.w = cvt_pk_bf16(z1[2], z1[3]);
;                     if (!dry && xb) *(u32x4*)(xb + off) = w;
.Lre_nx0_0:
	v_pk_add_f32 v[110:111], v[110:111], v[136:137]
	v_pk_add_f32 v[112:113], v[112:113], v[138:139]
	v_pk_add_f32 v[102:103], v[102:103], v[136:137]
	v_pk_add_f32 v[104:105], v[104:105], v[138:139]
	s_add_u32 s44, s60, 0x10000
	s_addc_u32 s45, s61, 0
	v_pk_fma_f32 v[152:153], v[132:133], v[110:111], v[152:153]
	v_pk_fma_f32 v[154:155], v[134:135], v[112:113], v[154:155]
	v_pk_fma_f32 v[156:157], v[132:133], v[102:103], v[156:157]
	v_pk_fma_f32 v[158:159], v[134:135], v[104:105], v[158:159]
	global_store_dwordx4 v180, v[152:155], s[44:45] sc1
	global_store_dwordx4 v181, v[156:159], s[44:45] sc1
	v_pk_mul_f32 v[110:111], v[140:141], v[152:153]
	v_pk_mul_f32 v[112:113], v[142:143], v[154:155]
	v_pk_mul_f32 v[102:103], v[140:141], v[156:157]
	v_pk_mul_f32 v[104:105], v[142:143], v[158:159]
	v_mul_f32_e32 v231, v153, v153
	v_mul_f32_e32 v244, v155, v155
	v_fmac_f32_e32 v231, v152, v152
	v_fmac_f32_e32 v244, v154, v154
	v_cvt_pk_bf16_f32 v110, v110, v111
	v_cvt_pk_bf16_f32 v111, v112, v113
	v_add_f32_e32 v112, v231, v244
	v_cvt_pk_bf16_f32 v102, v102, v103
	v_cvt_pk_bf16_f32 v103, v104, v105
	v_mul_f32_e32 v231, v157, v157
	v_mul_f32_e32 v244, v159, v159
	v_fmac_f32_e32 v231, v156, v156
	v_fmac_f32_e32 v244, v158, v158
	s_add_u32 s100, s64, 0x8000
	s_addc_u32 s101, s65, 0
	v_add_f32_e32 v104, v231, v244
	s_cbranch_vccz .Lre_nx0_1
	global_store_dwordx2 v194, v[110:111], s[100:101]
	global_store_dwordx2 v195, v[102:103], s[100:101]
.Lre_nx0_1:
	v_pk_add_f32 v[94:95], v[94:95], v[136:137]
	v_pk_add_f32 v[96:97], v[96:97], v[138:139]
	v_pk_add_f32 v[86:87], v[86:87], v[136:137]
	v_pk_add_f32 v[88:89], v[88:89], v[138:139]
	s_add_u32 s44, s60, 0x20000
	s_addc_u32 s45, s61, 0
	v_pk_fma_f32 v[160:161], v[132:133], v[94:95], v[160:161]
	v_pk_fma_f32 v[162:163], v[134:135], v[96:97], v[162:163]
	v_pk_fma_f32 v[164:165], v[132:133], v[86:87], v[164:165]
	v_pk_fma_f32 v[166:167], v[134:135], v[88:89], v[166:167]
	global_store_dwordx4 v180, v[160:163], s[44:45] sc1
	global_store_dwordx4 v181, v[164:167], s[44:45] sc1
	v_pk_mul_f32 v[94:95], v[140:141], v[160:161]
	v_pk_mul_f32 v[96:97], v[142:143], v[162:163]
	v_pk_mul_f32 v[86:87], v[140:141], v[164:165]
	v_pk_mul_f32 v[88:89], v[142:143], v[166:167]
	v_mul_f32_e32 v231, v161, v161
	v_mul_f32_e32 v244, v163, v163
	v_fmac_f32_e32 v231, v160, v160
	v_fmac_f32_e32 v244, v162, v162
	v_cvt_pk_bf16_f32 v94, v94, v95
	v_cvt_pk_bf16_f32 v95, v96, v97
	v_add_f32_e32 v96, v231, v244
	v_cvt_pk_bf16_f32 v86, v86, v87
	v_cvt_pk_bf16_f32 v87, v88, v89
	v_mul_f32_e32 v231, v165, v165
	v_mul_f32_e32 v244, v167, v167
	v_fmac_f32_e32 v231, v164, v164
	v_fmac_f32_e32 v244, v166, v166
	s_add_u32 s100, s64, 0x10000
	s_addc_u32 s101, s65, 0
	v_add_f32_e32 v88, v231, v244
	s_cbranch_vccz .Lre_nx0_2
	global_store_dwordx2 v194, v[94:95], s[100:101]
	global_store_dwordx2 v195, v[86:87], s[100:101]
.Lre_nx0_2:
	v_pk_add_f32 v[78:79], v[78:79], v[136:137]
	v_pk_add_f32 v[80:81], v[80:81], v[138:139]
	v_pk_add_f32 v[70:71], v[70:71], v[136:137]
	v_pk_add_f32 v[72:73], v[72:73], v[138:139]
	s_add_u32 s44, s60, 0x30000
	s_addc_u32 s45, s61, 0
	v_pk_fma_f32 v[168:169], v[132:133], v[78:79], v[168:169]
	v_pk_fma_f32 v[170:171], v[134:135], v[80:81], v[170:171]
	v_pk_fma_f32 v[172:173], v[132:133], v[70:71], v[172:173]
	v_pk_fma_f32 v[174:175], v[134:135], v[72:73], v[174:175]
	global_store_dwordx4 v180, v[168:171], s[44:45] sc1
	global_store_dwordx4 v181, v[172:175], s[44:45] sc1
	v_pk_mul_f32 v[78:79], v[140:141], v[168:169]
	v_pk_mul_f32 v[80:81], v[142:143], v[170:171]
	v_pk_mul_f32 v[70:71], v[140:141], v[172:173]
	v_pk_mul_f32 v[72:73], v[142:143], v[174:175]
	v_mul_f32_e32 v231, v169, v169
	v_mul_f32_e32 v244, v171, v171
	v_fmac_f32_e32 v231, v168, v168
	v_fmac_f32_e32 v244, v170, v170
	v_cvt_pk_bf16_f32 v78, v78, v79
	v_cvt_pk_bf16_f32 v79, v80, v81
	v_add_f32_e32 v80, v231, v244
	v_cvt_pk_bf16_f32 v70, v70, v71
	v_cvt_pk_bf16_f32 v71, v72, v73
	v_mul_f32_e32 v231, v173, v173
	v_mul_f32_e32 v244, v175, v175
	v_fmac_f32_e32 v231, v172, v172
	v_fmac_f32_e32 v244, v174, v174
	s_add_u32 s100, s64, 0x18000
	s_addc_u32 s101, s65, 0
	v_add_f32_e32 v72, v231, v244
	s_cbranch_vccz .Lre_nx0_3
	global_store_dwordx2 v194, v[78:79], s[100:101]
	global_store_dwordx2 v195, v[70:71], s[100:101]

; __device__ __forceinline__ unsigned cvt_pk_bf16(float lo, float hi) { unsigned r; asm volatile("v_cvt_pk_bf16_f32 %0, %1, %2" : "=v"(r) : "v"(lo), "v"(hi)); return r; }
;     __device__ __forceinline__ void operator()(const f32x4 (&acc)[2][2][4][2], const Unit& u, int wr, int wc, int fr, int fq) const {
;     ...
;                 for (int m = 0; m < 4; ++m) {
;                     const unsigned off = (unsigned)(row0 + ai * HALF + m * 16) * 1024u + (unsigned)c;
;                     const f32x4 x0 = xa[m][0], x1 = xa[m][1];
;                     const f32x4 y0 = x0 + g0 * (acc[ai][bj][m][0] + b0), y1 = x1 + g1 * (acc[ai][bj][m][1] + b1);
;                     if (!dry) { *(f32x4*)(xnew + off) = y0; *(f32x4*)(xnew + off + 4) = y1; }
;                     ss[ai][m] += (y0[0] * y0[0] + y0[1] * y0[1]) + (y0[2] * y0[2] + y0[3] * y0[3]) + (y1[0] * y1[0] + y1[1] * y1[1]) + (y1[2] * y1[2] + y1[3] * y1[3]);
;                     asm volatile("" : "+v"(ss[ai][m]));
;                     const f32x4 z0 = y0 * n0, z1 = y1 * n1;
;                     u32x4 w; w.x = cvt_pk_bf16(z0[0], z0[1]); w.y = cvt_pk_bf16(z0[2], z0[3]); w.z = cvt_pk_bf16(z1[0], z1[1]); w.w = cvt_pk_bf16(z1[2], z1[3]);
;                     if (!dry && xb) *(u32x4*)(xb + off) = w;
.Lre_w1_b:
	v_pk_add_f32 v[62:63], v[62:63], v[136:137]
	v_pk_add_f32 v[64:65], v[64:65], v[138:139]
	v_pk_add_f32 v[54:55], v[54:55], v[136:137]
	v_pk_add_f32 v[56:57], v[56:57], v[138:139]
	s_add_u32 s44, s60, 0x80000
	s_addc_u32 s45, s61, 0
	v_pk_fma_f32 v[176:177], v[132:133], v[62:63], v[176:177]
	v_pk_fma_f32 v[178:179], v[134:135], v[64:65], v[178:179]
	v_pk_fma_f32 v[196:197], v[132:133], v[54:55], v[196:197]
	v_pk_fma_f32 v[198:199], v[134:135], v[56:57], v[198:199]
	global_store_dwordx4 v180, v[176:179], s[44:45] sc1
	global_store_dwordx4 v181, v[196:199], s[44:45] sc1
	v_pk_mul_f32 v[62:63], v[140:141], v[176:177]
	v_pk_mul_f32 v[64:65], v[142:143], v[178:179]
	v_pk_mul_f32 v[54:55], v[140:141], v[196:197]
	v_pk_mul_f32 v[56:57], v[142:143], v[198:199]
	v_mul_f32_e32 v231, v177, v177
	v_mul_f32_e32 v244, v179, v179
	v_fmac_f32_e32 v231, v176, v176
	v_fmac_f32_e32 v244, v178, v178
	v_cvt_pk_bf16_f32 v62, v62, v63
	v_cvt_pk_bf16_f32 v63, v64, v65
	v_add_f32_e32 v64, v231, v244
	v_cvt_pk_bf16_f32 v54, v54, v55
	v_cvt_pk_bf16_f32 v55, v56, v57
	v_mul_f32_e32 v231, v197, v197
	v_mul_f32_e32 v244, v199, v199
	v_fmac_f32_e32 v231, v196, v196
	v_fmac_f32_e32 v244, v198, v198
	s_add_u32 s100, s64, 0x40000
	s_addc_u32 s101, s65, 0
	v_add_f32_e32 v56, v231, v244
	s_cbranch_vccz .Lre_nx1_0
	global_store_dwordx2 v194, v[62:63], s[100:101]
	global_store_dwordx2 v195, v[54:55], s[100:101]
.Lre_nx1_0:
	v_pk_add_f32 v[46:47], v[46:47], v[136:137]
	v_pk_add_f32 v[48:49], v[48:49], v[138:139]
	v_pk_add_f32 v[38:39], v[38:39], v[136:137]
	v_pk_add_f32 v[40:41], v[40:41], v[138:139]
	s_add_u32 s44, s60, 0x90000
	s_addc_u32 s45, s61, 0
	v_pk_fma_f32 v[200:201], v[132:133], v[46:47], v[200:201]
	v_pk_fma_f32 v[202:203], v[134:135], v[48:49], v[202:203]
	v_pk_fma_f32 v[204:205], v[132:133], v[38:39], v[204:205]
	v_pk_fma_f32 v[206:207], v[134:135], v[40:41], v[206:207]
	global_store_dwordx4 v180, v[200:203], s[44:45] sc1
	global_store_dwordx4 v181, v[204:207], s[44:45] sc1
	v_pk_mul_f32 v[46:47], v[140:141], v[200:201]
	v_pk_mul_f32 v[48:49], v[142:143], v[202:203]
	v_pk_mul_f32 v[38:39], v[140:141], v[204:205]
	v_pk_mul_f32 v[40:41], v[142:143], v[206:207]
	v_mul_f32_e32 v231, v201, v201
	v_mul_f32_e32 v244, v203, v203
	v_fmac_f32_e32 v231, v200, v200
	v_fmac_f32_e32 v244, v202, v202
	v_cvt_pk_bf16_f32 v46, v46, v47
	v_cvt_pk_bf16_f32 v47, v48, v49
	v_add_f32_e32 v48, v231, v244
	v_cvt_pk_bf16_f32 v38, v38, v39
	v_cvt_pk_bf16_f32 v39, v40, v41
	v_mul_f32_e32 v231, v205, v205
	v_mul_f32_e32 v244, v207, v207
	v_fmac_f32_e32 v231, v204, v204
	v_fmac_f32_e32 v244, v206, v206
	s_add_u32 s100, s64, 0x48000
	s_addc_u32 s101, s65, 0
	v_add_f32_e32 v40, v231, v244
	s_cbranch_vccz .Lre_nx1_1
	global_store_dwordx2 v194, v[46:47], s[100:101]
	global_store_dwordx2 v195, v[38:39], s[100:101]
.Lre_nx1_1:
	v_pk_add_f32 v[30:31], v[30:31], v[136:137]
	v_pk_add_f32 v[32:33], v[32:33], v[138:139]
	v_pk_add_f32 v[22:23], v[22:23], v[136:137]
	v_pk_add_f32 v[24:25], v[24:25], v[138:139]
	s_add_u32 s44, s60, 0xa0000
	s_addc_u32 s45, s61, 0
	v_pk_fma_f32 v[208:209], v[132:133], v[30:31], v[208:209]
	v_pk_fma_f32 v[210:211], v[134:135], v[32:33], v[210:211]
	v_pk_fma_f32 v[232:233], v[132:133], v[22:23], v[232:233]
	v_pk_fma_f32 v[234:235], v[134:135], v[24:25], v[234:235]
	global_store_dwordx4 v180, v[208:211], s[44:45] sc1
	global_store_dwordx4 v181, v[232:235], s[44:45] sc1
	v_pk_mul_f32 v[30:31], v[140:141], v[208:209]
	v_pk_mul_f32 v[32:33], v[142:143], v[210:211]
	v_pk_mul_f32 v[22:23], v[140:141], v[232:233]
	v_pk_mul_f32 v[24:25], v[142:143], v[234:235]
	v_mul_f32_e32 v231, v209, v209
	v_mul_f32_e32 v244, v211, v211
	v_fmac_f32_e32 v231, v208, v208
	v_fmac_f32_e32 v244, v210, v210
	v_cvt_pk_bf16_f32 v30, v30, v31
	v_cvt_pk_bf16_f32 v31, v32, v33
	v_add_f32_e32 v32, v231, v244
	v_cvt_pk_bf16_f32 v22, v22, v23
	v_cvt_pk_bf16_f32 v23, v24, v25
	v_mul_f32_e32 v231, v233, v233
	v_mul_f32_e32 v244, v235, v235
	v_fmac_f32_e32 v231, v232, v232
	v_fmac_f32_e32 v244, v234, v234
	s_add_u32 s100, s64, 0x50000
	s_addc_u32 s101, s65, 0
	v_add_f32_e32 v24, v231, v244
	s_cbranch_vccz .Lre_nx1_2
	global_store_dwordx2 v194, v[30:31], s[100:101]
	global_store_dwordx2 v195, v[22:23], s[100:101]
.Lre_nx1_2:
	v_pk_add_f32 v[14:15], v[14:15], v[136:137]
	v_pk_add_f32 v[16:17], v[16:17], v[138:139]
	v_pk_add_f32 v[6:7], v[6:7], v[136:137]
	v_pk_add_f32 v[8:9], v[8:9], v[138:139]
	s_add_u32 s44, s60, 0xb0000
	s_addc_u32 s45, s61, 0
	v_pk_fma_f32 v[236:237], v[132:133], v[14:15], v[236:237]
	v_pk_fma_f32 v[238:239], v[134:135], v[16:17], v[238:239]
	v_pk_fma_f32 v[240:241], v[132:133], v[6:7], v[240:241]
	v_pk_fma_f32 v[242:243], v[134:135], v[8:9], v[242:243]
	global_store_dwordx4 v180, v[236:239], s[44:45] sc1
	global_store_dwordx4 v181, v[240:243], s[44:45] sc1
	v_pk_mul_f32 v[14:15], v[140:141], v[236:237]
	v_pk_mul_f32 v[16:17], v[142:143], v[238:239]
	v_pk_mul_f32 v[6:7], v[140:141], v[240:241]
	v_pk_mul_f32 v[8:9], v[142:143], v[242:243]
	v_mul_f32_e32 v231, v237, v237
	v_mul_f32_e32 v244, v239, v239
	v_fmac_f32_e32 v231, v236, v236
	v_fmac_f32_e32 v244, v238, v238
	v_cvt_pk_bf16_f32 v14, v14, v15
	v_cvt_pk_bf16_f32 v15, v16, v17
	v_add_f32_e32 v16, v231, v244
	v_cvt_pk_bf16_f32 v6, v6, v7
	v_cvt_pk_bf16_f32 v7, v8, v9
	v_mul_f32_e32 v231, v241, v241
	v_mul_f32_e32 v244, v243, v243
	v_fmac_f32_e32 v231, v240, v240
	v_fmac_f32_e32 v244, v242, v242
	s_add_u32 s100, s64, 0x58000
	s_addc_u32 s101, s65, 0
	v_add_f32_e32 v8, v231, v244
	s_cbranch_vccz .Lre_nx1_3
	global_store_dwordx2 v194, v[14:15], s[100:101]
	global_store_dwordx2 v195, v[6:7], s[100:101]

; __device__ __forceinline__ unsigned cvt_pk_bf16(float lo, float hi) { unsigned r; asm volatile("v_cvt_pk_bf16_f32 %0, %1, %2" : "=v"(r) : "v"(lo), "v"(hi)); return r; }
;     __device__ __forceinline__ void operator()(const f32x4 (&acc)[2][2][4][2], const Unit& u, int wr, int wc, int fr, int fq) const {
;     ...
;                 for (int m = 0; m < 4; ++m) {
;                     const unsigned off = (unsigned)(row0 + ai * HALF + m * 16) * 1024u + (unsigned)c;
;                     const f32x4 x0 = xa[m][0], x1 = xa[m][1];
;                     const f32x4 y0 = x0 + g0 * (acc[ai][bj][m][0] + b0), y1 = x1 + g1 * (acc[ai][bj][m][1] + b1);
;                     if (!dry) { *(f32x4*)(xnew + off) = y0; *(f32x4*)(xnew + off + 4) = y1; }
;                     ss[ai][m] += (y0[0] * y0[0] + y0[1] * y0[1]) + (y0[2] * y0[2] + y0[3] * y0[3]) + (y1[0] * y1[0] + y1[1] * y1[1]) + (y1[2] * y1[2] + y1[3] * y1[3]);
;                     asm volatile("" : "+v"(ss[ai][m]));
;                     const f32x4 z0 = y0 * n0, z1 = y1 * n1;
;                     u32x4 w; w.x = cvt_pk_bf16(z0[0], z0[1]); w.y = cvt_pk_bf16(z0[2], z0[3]); w.z = cvt_pk_bf16(z1[0], z1[1]); w.w = cvt_pk_bf16(z1[2], z1[3]);
;                     if (!dry && xb) *(u32x4*)(xb + off) = w;
.Lre_w2_b:
	v_pk_add_f32 v[118:119], v[118:119], v[216:217]
	v_pk_add_f32 v[120:121], v[120:121], v[218:219]
	v_pk_add_f32 v[114:115], v[114:115], v[216:217]
	v_pk_add_f32 v[116:117], v[116:117], v[218:219]
	s_add_u32 s44, s60, 0x200
	s_addc_u32 s45, s61, 0
	v_pk_fma_f32 v[144:145], v[212:213], v[118:119], v[144:145]
	v_pk_fma_f32 v[146:147], v[214:215], v[120:121], v[146:147]
	v_pk_fma_f32 v[148:149], v[212:213], v[114:115], v[148:149]
	v_pk_fma_f32 v[150:151], v[214:215], v[116:117], v[150:151]
	global_store_dwordx4 v180, v[144:147], s[44:45] sc1
	global_store_dwordx4 v181, v[148:151], s[44:45] sc1
	v_pk_mul_f32 v[118:119], v[220:221], v[144:145]
	v_pk_mul_f32 v[120:121], v[222:223], v[146:147]
	v_pk_mul_f32 v[114:115], v[220:221], v[148:149]
	v_pk_mul_f32 v[116:117], v[222:223], v[150:151]
	v_mul_f32_e32 v231, v145, v145
	v_mul_f32_e32 v244, v147, v147
	v_fmac_f32_e32 v231, v144, v144
	v_fmac_f32_e32 v244, v146, v146
	v_cvt_pk_bf16_f32 v118, v118, v119
	v_cvt_pk_bf16_f32 v119, v120, v121
	v_add_f32_e32 v231, v231, v244
	v_cvt_pk_bf16_f32 v114, v114, v115
	v_cvt_pk_bf16_f32 v115, v116, v117
	v_add_f32_e32 v128, v128, v231
	v_mul_f32_e32 v231, v149, v149
	v_mul_f32_e32 v244, v151, v151
	v_fmac_f32_e32 v231, v148, v148
	v_fmac_f32_e32 v244, v150, v150
	s_add_u32 s100, s64, 0x100
	s_addc_u32 s101, s65, 0
	v_add_f32_e32 v231, v231, v244
	v_add_f32_e32 v124, v124, v231
	s_cbranch_vccz .Lre_nx2_0
	global_store_dwordx2 v194, v[118:119], s[100:101]
	global_store_dwordx2 v195, v[114:115], s[100:101]
.Lre_nx2_0:
	v_pk_add_f32 v[106:107], v[106:107], v[216:217]
	v_pk_add_f32 v[108:109], v[108:109], v[218:219]
	v_pk_add_f32 v[98:99], v[98:99], v[216:217]
	v_pk_add_f32 v[100:101], v[100:101], v[218:219]
	s_add_u32 s44, s60, 0x10200
	s_addc_u32 s45, s61, 0
	v_pk_fma_f32 v[152:153], v[212:213], v[106:107], v[152:153]
	v_pk_fma_f32 v[154:155], v[214:215], v[108:109], v[154:155]
	v_pk_fma_f32 v[156:157], v[212:213], v[98:99], v[156:157]
	v_pk_fma_f32 v[158:159], v[214:215], v[100:101], v[158:159]
	global_store_dwordx4 v180, v[152:155], s[44:45] sc1
	global_store_dwordx4 v181, v[156:159], s[44:45] sc1
	v_pk_mul_f32 v[106:107], v[220:221], v[152:153]
	v_pk_mul_f32 v[108:109], v[222:223], v[154:155]
	v_pk_mul_f32 v[98:99], v[220:221], v[156:157]
	v_pk_mul_f32 v[100:101], v[222:223], v[158:159]
	v_mul_f32_e32 v231, v153, v153
	v_mul_f32_e32 v244, v155, v155
	v_fmac_f32_e32 v231, v152, v152
	v_fmac_f32_e32 v244, v154, v154
	v_cvt_pk_bf16_f32 v106, v106, v107
	v_cvt_pk_bf16_f32 v107, v108, v109
	v_add_f32_e32 v231, v231, v244
	v_cvt_pk_bf16_f32 v98, v98, v99
	v_cvt_pk_bf16_f32 v99, v100, v101
	v_add_f32_e32 v112, v112, v231
	v_mul_f32_e32 v231, v157, v157
	v_mul_f32_e32 v244, v159, v159
	v_fmac_f32_e32 v231, v156, v156
	v_fmac_f32_e32 v244, v158, v158
	s_add_u32 s100, s64, 0x8100
	s_addc_u32 s101, s65, 0
	v_add_f32_e32 v231, v231, v244
	v_add_f32_e32 v104, v104, v231
	s_cbranch_vccz .Lre_nx2_1
	global_store_dwordx2 v194, v[106:107], s[100:101]
	global_store_dwordx2 v195, v[98:99], s[100:101]
.Lre_nx2_1:
	v_pk_add_f32 v[90:91], v[90:91], v[216:217]
	v_pk_add_f32 v[92:93], v[92:93], v[218:219]
	v_pk_add_f32 v[82:83], v[82:83], v[216:217]
	v_pk_add_f32 v[84:85], v[84:85], v[218:219]
	s_add_u32 s44, s60, 0x20200
	s_addc_u32 s45, s61, 0
	v_pk_fma_f32 v[160:161], v[212:213], v[90:91], v[160:161]
	v_pk_fma_f32 v[162:163], v[214:215], v[92:93], v[162:163]
	v_pk_fma_f32 v[164:165], v[212:213], v[82:83], v[164:165]
	v_pk_fma_f32 v[166:167], v[214:215], v[84:85], v[166:167]
	global_store_dwordx4 v180, v[160:163], s[44:45] sc1
	global_store_dwordx4 v181, v[164:167], s[44:45] sc1
	v_pk_mul_f32 v[90:91], v[220:221], v[160:161]
	v_pk_mul_f32 v[92:93], v[222:223], v[162:163]
	v_pk_mul_f32 v[82:83], v[220:221], v[164:165]
	v_pk_mul_f32 v[84:85], v[222:223], v[166:167]
	v_mul_f32_e32 v231, v161, v161
	v_mul_f32_e32 v244, v163, v163
	v_fmac_f32_e32 v231, v160, v160
	v_fmac_f32_e32 v244, v162, v162
	v_cvt_pk_bf16_f32 v90, v90, v91
	v_cvt_pk_bf16_f32 v91, v92, v93
	v_add_f32_e32 v231, v231, v244
	v_cvt_pk_bf16_f32 v82, v82, v83
	v_cvt_pk_bf16_f32 v83, v84, v85
	v_add_f32_e32 v96, v96, v231
	v_mul_f32_e32 v231, v165, v165
	v_mul_f32_e32 v244, v167, v167
	v_fmac_f32_e32 v231, v164, v164
	v_fmac_f32_e32 v244, v166, v166
	s_add_u32 s100, s64, 0x10100
	s_addc_u32 s101, s65, 0
	v_add_f32_e32 v231, v231, v244
	v_add_f32_e32 v88, v88, v231
	s_cbranch_vccz .Lre_nx2_2
	global_store_dwordx2 v194, v[90:91], s[100:101]
	global_store_dwordx2 v195, v[82:83], s[100:101]
.Lre_nx2_2:
	v_pk_add_f32 v[74:75], v[74:75], v[216:217]
	v_pk_add_f32 v[76:77], v[76:77], v[218:219]
	v_pk_add_f32 v[66:67], v[66:67], v[216:217]
	v_pk_add_f32 v[68:69], v[68:69], v[218:219]
	s_add_u32 s44, s60, 0x30200
	s_addc_u32 s45, s61, 0
	v_pk_fma_f32 v[168:169], v[212:213], v[74:75], v[168:169]
	v_pk_fma_f32 v[170:171], v[214:215], v[76:77], v[170:171]
	v_pk_fma_f32 v[172:173], v[212:213], v[66:67], v[172:173]
	v_pk_fma_f32 v[174:175], v[214:215], v[68:69], v[174:175]
	global_store_dwordx4 v180, v[168:171], s[44:45] sc1
	global_store_dwordx4 v181, v[172:175], s[44:45] sc1
	v_pk_mul_f32 v[74:75], v[220:221], v[168:169]
	v_pk_mul_f32 v[76:77], v[222:223], v[170:171]
	v_pk_mul_f32 v[66:67], v[220:221], v[172:173]
	v_pk_mul_f32 v[68:69], v[222:223], v[174:175]
	v_mul_f32_e32 v231, v169, v169
	v_mul_f32_e32 v244, v171, v171
	v_fmac_f32_e32 v231, v168, v168
	v_fmac_f32_e32 v244, v170, v170
	v_cvt_pk_bf16_f32 v74, v74, v75
	v_cvt_pk_bf16_f32 v75, v76, v77
	v_add_f32_e32 v231, v231, v244
	v_cvt_pk_bf16_f32 v66, v66, v67
	v_cvt_pk_bf16_f32 v67, v68, v69
	v_add_f32_e32 v80, v80, v231
	v_mul_f32_e32 v231, v173, v173
	v_mul_f32_e32 v244, v175, v175
	v_fmac_f32_e32 v231, v172, v172
	v_fmac_f32_e32 v244, v174, v174
	s_add_u32 s100, s64, 0x18100
	s_addc_u32 s101, s65, 0
	v_add_f32_e32 v231, v231, v244
	v_add_f32_e32 v72, v72, v231
	s_cbranch_vccz .Lre_nx2_3
	global_store_dwordx2 v194, v[74:75], s[100:101]
	global_store_dwordx2 v195, v[66:67], s[100:101]

; __device__ __forceinline__ unsigned cvt_pk_bf16(float lo, float hi) { unsigned r; asm volatile("v_cvt_pk_bf16_f32 %0, %1, %2" : "=v"(r) : "v"(lo), "v"(hi)); return r; }
;     __device__ __forceinline__ void operator()(const f32x4 (&acc)[2][2][4][2], const Unit& u, int wr, int wc, int fr, int fq) const {
;     ...
;                 for (int m = 0; m < 4; ++m) {
;                     const unsigned off = (unsigned)(row0 + ai * HALF + m * 16) * 1024u + (unsigned)c;
;                     const f32x4 x0 = xa[m][0], x1 = xa[m][1];
;                     const f32x4 y0 = x0 + g0 * (acc[ai][bj][m][0] + b0), y1 = x1 + g1 * (acc[ai][bj][m][1] + b1);
;                     if (!dry) { *(f32x4*)(xnew + off) = y0; *(f32x4*)(xnew + off + 4) = y1; }
;                     ss[ai][m] += (y0[0] * y0[0] + y0[1] * y0[1]) + (y0[2] * y0[2] + y0[3] * y0[3]) + (y1[0] * y1[0] + y1[1] * y1[1]) + (y1[2] * y1[2] + y1[3] * y1[3]);
;                     asm volatile("" : "+v"(ss[ai][m]));
;                     const f32x4 z0 = y0 * n0, z1 = y1 * n1;
;                     u32x4 w; w.x = cvt_pk_bf16(z0[0], z0[1]); w.y = cvt_pk_bf16(z0[2], z0[3]); w.z = cvt_pk_bf16(z1[0], z1[1]); w.w = cvt_pk_bf16(z1[2], z1[3]);
;                     if (!dry && xb) *(u32x4*)(xb + off) = w;
.Lre_w3_b:
	v_pk_add_f32 v[58:59], v[58:59], v[216:217]
	v_pk_add_f32 v[60:61], v[60:61], v[218:219]
	v_pk_add_f32 v[50:51], v[50:51], v[216:217]
	v_pk_add_f32 v[52:53], v[52:53], v[218:219]
	s_add_u32 s44, s60, 0x80200
	s_addc_u32 s45, s61, 0
	v_pk_fma_f32 v[176:177], v[212:213], v[58:59], v[176:177]
	v_pk_fma_f32 v[178:179], v[214:215], v[60:61], v[178:179]
	v_pk_fma_f32 v[196:197], v[212:213], v[50:51], v[196:197]
	v_pk_fma_f32 v[198:199], v[214:215], v[52:53], v[198:199]
	global_store_dwordx4 v180, v[176:179], s[44:45] sc1
	global_store_dwordx4 v181, v[196:199], s[44:45] sc1
	v_pk_mul_f32 v[58:59], v[220:221], v[176:177]
	v_pk_mul_f32 v[60:61], v[222:223], v[178:179]
	v_pk_mul_f32 v[50:51], v[220:221], v[196:197]
	v_pk_mul_f32 v[52:53], v[222:223], v[198:199]
	v_mul_f32_e32 v231, v177, v177
	v_mul_f32_e32 v244, v179, v179
	v_fmac_f32_e32 v231, v176, v176
	v_fmac_f32_e32 v244, v178, v178
	v_cvt_pk_bf16_f32 v58, v58, v59
	v_cvt_pk_bf16_f32 v59, v60, v61
	v_add_f32_e32 v231, v231, v244
	v_cvt_pk_bf16_f32 v50, v50, v51
	v_cvt_pk_bf16_f32 v51, v52, v53
	v_add_f32_e32 v64, v64, v231
	v_mul_f32_e32 v231, v197, v197
	v_mul_f32_e32 v244, v199, v199
	v_fmac_f32_e32 v231, v196, v196
	v_fmac_f32_e32 v244, v198, v198
	s_add_u32 s100, s64, 0x40100
	s_addc_u32 s101, s65, 0
	v_add_f32_e32 v231, v231, v244
	v_add_f32_e32 v56, v56, v231
	s_cbranch_vccz .Lre_nx3_0
	global_store_dwordx2 v194, v[58:59], s[100:101]
	global_store_dwordx2 v195, v[50:51], s[100:101]
.Lre_nx3_0:
	v_pk_add_f32 v[42:43], v[42:43], v[216:217]
	v_pk_add_f32 v[44:45], v[44:45], v[218:219]
	v_pk_add_f32 v[34:35], v[34:35], v[216:217]
	v_pk_add_f32 v[36:37], v[36:37], v[218:219]
	s_add_u32 s44, s60, 0x90200
	s_addc_u32 s45, s61, 0
	v_pk_fma_f32 v[200:201], v[212:213], v[42:43], v[200:201]
	v_pk_fma_f32 v[202:203], v[214:215], v[44:45], v[202:203]
	v_pk_fma_f32 v[204:205], v[212:213], v[34:35], v[204:205]
	v_pk_fma_f32 v[206:207], v[214:215], v[36:37], v[206:207]
	global_store_dwordx4 v180, v[200:203], s[44:45] sc1
	global_store_dwordx4 v181, v[204:207], s[44:45] sc1
	v_pk_mul_f32 v[42:43], v[220:221], v[200:201]
	v_pk_mul_f32 v[44:45], v[222:223], v[202:203]
	v_pk_mul_f32 v[34:35], v[220:221], v[204:205]
	v_pk_mul_f32 v[36:37], v[222:223], v[206:207]
	v_mul_f32_e32 v231, v201, v201
	v_mul_f32_e32 v244, v203, v203
	v_fmac_f32_e32 v231, v200, v200
	v_fmac_f32_e32 v244, v202, v202
	v_cvt_pk_bf16_f32 v42, v42, v43
	v_cvt_pk_bf16_f32 v43, v44, v45
	v_add_f32_e32 v231, v231, v244
	v_cvt_pk_bf16_f32 v34, v34, v35
	v_cvt_pk_bf16_f32 v35, v36, v37
	v_add_f32_e32 v48, v48, v231
	v_mul_f32_e32 v231, v205, v205
	v_mul_f32_e32 v244, v207, v207
	v_fmac_f32_e32 v231, v204, v204
	v_fmac_f32_e32 v244, v206, v206
	s_add_u32 s100, s64, 0x48100
	s_addc_u32 s101, s65, 0
	v_add_f32_e32 v231, v231, v244
	v_add_f32_e32 v40, v40, v231
	s_cbranch_vccz .Lre_nx3_1
	global_store_dwordx2 v194, v[42:43], s[100:101]
	global_store_dwordx2 v195, v[34:35], s[100:101]
.Lre_nx3_1:
	v_pk_add_f32 v[26:27], v[26:27], v[216:217]
	v_pk_add_f32 v[28:29], v[28:29], v[218:219]
	v_pk_add_f32 v[18:19], v[18:19], v[216:217]
	v_pk_add_f32 v[20:21], v[20:21], v[218:219]
	s_add_u32 s44, s60, 0xa0200
	s_addc_u32 s45, s61, 0
	v_pk_fma_f32 v[208:209], v[212:213], v[26:27], v[208:209]
	v_pk_fma_f32 v[210:211], v[214:215], v[28:29], v[210:211]
	v_pk_fma_f32 v[232:233], v[212:213], v[18:19], v[232:233]
	v_pk_fma_f32 v[234:235], v[214:215], v[20:21], v[234:235]
	global_store_dwordx4 v180, v[208:211], s[44:45] sc1
	global_store_dwordx4 v181, v[232:235], s[44:45] sc1
	v_pk_mul_f32 v[26:27], v[220:221], v[208:209]
	v_pk_mul_f32 v[28:29], v[222:223], v[210:211]
	v_pk_mul_f32 v[18:19], v[220:221], v[232:233]
	v_pk_mul_f32 v[20:21], v[222:223], v[234:235]
	v_mul_f32_e32 v231, v209, v209
	v_mul_f32_e32 v244, v211, v211
	v_fmac_f32_e32 v231, v208, v208
	v_fmac_f32_e32 v244, v210, v210
	v_cvt_pk_bf16_f32 v26, v26, v27
	v_cvt_pk_bf16_f32 v27, v28, v29
	v_add_f32_e32 v231, v231, v244
	v_cvt_pk_bf16_f32 v18, v18, v19
	v_cvt_pk_bf16_f32 v19, v20, v21
	v_add_f32_e32 v32, v32, v231
	v_mul_f32_e32 v231, v233, v233
	v_mul_f32_e32 v244, v235, v235
	v_fmac_f32_e32 v231, v232, v232
	v_fmac_f32_e32 v244, v234, v234
	s_add_u32 s100, s64, 0x50100
	s_addc_u32 s101, s65, 0
	v_add_f32_e32 v231, v231, v244
	v_add_f32_e32 v24, v24, v231
	s_cbranch_vccz .Lre_nx3_2
	global_store_dwordx2 v194, v[26:27], s[100:101]
	global_store_dwordx2 v195, v[18:19], s[100:101]
.Lre_nx3_2:
	v_pk_add_f32 v[10:11], v[10:11], v[216:217]
	v_pk_add_f32 v[12:13], v[12:13], v[218:219]
	v_pk_add_f32 v[2:3], v[2:3], v[216:217]
	v_pk_add_f32 v[4:5], v[4:5], v[218:219]
	s_add_u32 s44, s60, 0xb0200
	s_addc_u32 s45, s61, 0
	v_pk_fma_f32 v[236:237], v[212:213], v[10:11], v[236:237]
	v_pk_fma_f32 v[238:239], v[214:215], v[12:13], v[238:239]
	v_pk_fma_f32 v[240:241], v[212:213], v[2:3], v[240:241]
	v_pk_fma_f32 v[242:243], v[214:215], v[4:5], v[242:243]
	global_store_dwordx4 v180, v[236:239], s[44:45] sc1
	global_store_dwordx4 v181, v[240:243], s[44:45] sc1
	v_pk_mul_f32 v[10:11], v[220:221], v[236:237]
	v_pk_mul_f32 v[12:13], v[222:223], v[238:239]
	v_pk_mul_f32 v[2:3], v[220:221], v[240:241]
	v_pk_mul_f32 v[4:5], v[222:223], v[242:243]
	v_mul_f32_e32 v231, v237, v237
	v_mul_f32_e32 v244, v239, v239
	v_fmac_f32_e32 v231, v236, v236
	v_fmac_f32_e32 v244, v238, v238
	v_cvt_pk_bf16_f32 v10, v10, v11
	v_cvt_pk_bf16_f32 v11, v12, v13
	v_add_f32_e32 v231, v231, v244
	v_cvt_pk_bf16_f32 v2, v2, v3
	v_cvt_pk_bf16_f32 v3, v4, v5
	v_add_f32_e32 v16, v16, v231
	v_mul_f32_e32 v231, v241, v241
	v_mul_f32_e32 v244, v243, v243
	v_fmac_f32_e32 v231, v240, v240
	v_fmac_f32_e32 v244, v242, v242
	s_add_u32 s100, s64, 0x58100
	s_addc_u32 s101, s65, 0
	v_add_f32_e32 v231, v231, v244
	v_add_f32_e32 v8, v8, v231
	s_cbranch_vccz .Lre_nx3_3
	global_store_dwordx2 v194, v[10:11], s[100:101]
	global_store_dwordx2 v195, v[2:3], s[100:101]
